# P2b k-row staging: 8 serialized load->vmcnt(0)->ds_write steps replaced by 6 loads in flight with counted waits (uniform 0x2000 stride)
# baseline (speedup 1.0000x reference)
.LBB0_285:
	v_readlane_b32 s0, v254, 26
	s_and_b32 s2, s20, 3
	v_readlane_b32 s4, v252, 8
	v_mov_b32_e32 v0, s0
	s_waitcnt vmcnt(9)
	ds_read_b128 v[2:5], v0
	v_mov_b32_e32 v0, v1
	s_waitcnt lgkmcnt(0)
	v_readfirstlane_b32 s1, v2
	v_readfirstlane_b32 s0, v3
	s_add_u32 s16, s1, s60
	v_mbcnt_lo_u32_b32 v0, -1, v0
	s_addc_u32 s17, s0, s61
	v_readfirstlane_b32 s0, v4
	v_mbcnt_hi_u32_b32 v63, -1, v0
	v_readfirstlane_b32 s1, v5
	s_add_u32 s0, s0, s62
	s_addc_u32 s1, s1, s63
	s_waitcnt vmcnt(4)
	v_add_u32_e32 v70, s4, v63
	s_lshl_b32 s4, s20, 5
	v_add_u32_e32 v23, 0x200, v70
	v_add_u32_e32 v24, 0x400, v70
	v_add_u32_e32 v25, 0x600, v70
	s_and_b32 s4, s4, 0xffffff80
	v_readfirstlane_b32 s47, v70
	v_ashrrev_i32_e32 v62, 4, v70
	v_ashrrev_i32_e32 v65, 4, v23
	v_ashrrev_i32_e32 v66, 4, v24
	v_ashrrev_i32_e32 v67, 4, v25
	s_ashr_i32 s46, s47, 6
	s_lshl_b32 s5, s2, 22
	s_lshl_b32 s21, s2, 23
	v_add_u32_e32 v2, s4, v62
	v_add_u32_e32 v6, s4, v65
	v_add_u32_e32 v10, s4, v66
	s_waitcnt vmcnt(0)
	v_add_u32_e32 v14, s4, v67
	v_lshlrev_b32_e32 v64, 3, v63
	s_add_u32 s28, s18, s21
	v_ashrrev_i32_e32 v3, 31, v2
	v_ashrrev_i32_e32 v7, 31, v6
	v_ashrrev_i32_e32 v11, 31, v10
	v_ashrrev_i32_e32 v15, 31, v14
	v_ashrrev_i32_e32 v22, 2, v70
	v_and_b32_e32 v116, 0x78, v64
	s_addc_u32 s29, s6, 0
	v_lshlrev_b64 v[98:99], 9, v[2:3]
	v_lshlrev_b64 v[100:101], 9, v[6:7]
	v_lshlrev_b64 v[102:103], 9, v[10:11]
	v_lshlrev_b64 v[104:105], 9, v[14:15]
	v_add_u32_e32 v18, s4, v22
	v_lshl_add_u64 v[2:3], s[28:29], 0, v[98:99]
	v_lshlrev_b32_e32 v0, 1, v116
	v_lshl_add_u64 v[6:7], s[28:29], 0, v[100:101]
	v_lshl_add_u64 v[10:11], s[28:29], 0, v[102:103]
	v_lshl_add_u64 v[14:15], s[28:29], 0, v[104:105]
	v_ashrrev_i32_e32 v19, 31, v18
	v_lshl_add_u64 v[2:3], v[2:3], 0, v[0:1]
	v_lshl_add_u64 v[6:7], v[6:7], 0, v[0:1]
	v_lshl_add_u64 v[10:11], v[10:11], 0, v[0:1]
	v_lshl_add_u64 v[14:15], v[14:15], 0, v[0:1]
	v_lshlrev_b64 v[18:19], 6, v[18:19]
	v_lshlrev_b32_e32 v0, 4, v63
	v_lshl_add_u64 v[18:19], s[22:23], 0, v[18:19]
	v_and_b32_e32 v0, 48, v0
	v_lshl_add_u64 v[18:19], v[18:19], 0, v[0:1]
	s_barrier
	global_load_dwordx4 v[18:21], v[18:19], off
	s_mov_b32 s21, 0xb000000
	v_add_co_u32_e32 v2, vcc, s21, v2
	v_lshlrev_b32_e32 v22, 6, v22
	s_nop 0
	v_addc_co_u32_e32 v3, vcc, 0, v3, vcc
	v_add_co_u32_e32 v6, vcc, s21, v6
	v_add3_u32 v0, s89, v22, v0
	v_ashrrev_i32_e32 v26, 5, v70
	v_addc_co_u32_e32 v7, vcc, 0, v7, vcc
	v_add_co_u32_e32 v10, vcc, s21, v10
	s_add_u32 s36, s18, s5
	s_nop 0
	v_addc_co_u32_e32 v11, vcc, 0, v11, vcc
	v_and_b32_e32 v22, 31, v63
	s_addc_u32 s37, s6, 0
	v_add_co_u32_e32 v14, vcc, s21, v14
	s_mov_b32 s5, 0xa000000
	s_nop 0
	v_addc_co_u32_e32 v15, vcc, 0, v15, vcc
	v_lshlrev_b32_e32 v28, 2, v26
	v_lshlrev_b32_e32 v27, 9, v26
	v_and_b32_e32 v28, 12, v28
	v_ashrrev_i32_e32 v23, 5, v23
	v_and_b32_e32 v68, 63, v63
	v_lshlrev_b32_e32 v56, 3, v68
	global_load_dwordx4 v[2:5], v[2:3], off nt
	s_lshl_b32 s48, s46, 10
	global_load_dwordx4 v[6:9], v[6:7], off nt
	v_lshl_or_b32 v69, s46, 13, v56
	global_load_dwordx4 v[10:13], v[10:11], off nt
	v_lshlrev_b32_e32 v71, 1, v68
	global_load_dwordx4 v[14:17], v[14:15], off nt
	s_waitcnt vmcnt(4)
	ds_write_b128 v0, v[18:21]
	v_add_u32_e32 v18, s4, v26
	v_ashrrev_i32_e32 v19, 31, v18
	v_lshlrev_b64 v[18:19], 9, v[18:19]
	v_lshl_add_u64 v[18:19], s[36:37], 0, v[18:19]
	v_lshlrev_b32_e32 v0, 4, v22
	v_lshl_add_u64 v[18:19], v[18:19], 0, v[0:1]
	v_add_co_u32_e32 v18, vcc, s5, v18
	v_bfe_u32 v26, v26, 2, 2
	s_nop 0
	v_addc_co_u32_e32 v19, vcc, 0, v19, vcc
	v_mov_b32_e32 v232, v18
	v_mov_b32_e32 v233, v19
	s_mov_b32 s78, 0x2000
	s_mov_b32 s79, 0
	global_load_dwordx4 v[18:21], v[18:19], off nt
	v_lshl_add_u64 v[232:233], v[232:233], 0, s[78:79]
	global_load_dwordx4 v[212:215], v[232:233], off nt
	v_lshl_add_u64 v[232:233], v[232:233], 0, s[78:79]
	global_load_dwordx4 v[216:219], v[232:233], off nt
	v_lshl_add_u64 v[232:233], v[232:233], 0, s[78:79]
	global_load_dwordx4 v[220:223], v[232:233], off nt
	v_lshl_add_u64 v[232:233], v[232:233], 0, s[78:79]
	global_load_dwordx4 v[224:227], v[232:233], off nt
	v_lshl_add_u64 v[232:233], v[232:233], 0, s[78:79]
	global_load_dwordx4 v[228:231], v[232:233], off nt
	v_bitop3_b32 v26, v28, v22, v26 bitop3:0x36
	v_lshlrev_b32_e32 v26, 4, v26
	v_add3_u32 v26, 0, v26, v27
	v_lshlrev_b32_e32 v27, 2, v23
	v_and_b32_e32 v27, 12, v27
	s_waitcnt vmcnt(5)
	ds_write_b128 v26, v[18:21]
	v_lshl_add_u64 v[232:233], v[232:233], 0, s[78:79]
	global_load_dwordx4 v[18:21], v[232:233], off nt
	s_waitcnt vmcnt(5)
	ds_write_b128 v26, v[212:215] offset:8192
	v_lshl_add_u64 v[232:233], v[232:233], 0, s[78:79]
	global_load_dwordx4 v[212:215], v[232:233], off nt
	s_waitcnt vmcnt(5)
	ds_write_b128 v26, v[216:219] offset:16384
	s_waitcnt vmcnt(4)
	ds_write_b128 v26, v[220:223] offset:24576
	s_waitcnt vmcnt(3)
	ds_write_b128 v26, v[224:227] offset:32768
	s_waitcnt vmcnt(2)
	ds_write_b128 v26, v[228:231] offset:40960
	s_waitcnt vmcnt(1)
	ds_write_b128 v26, v[18:21] offset:49152
	s_waitcnt vmcnt(0)
	ds_write_b128 v26, v[212:215] offset:57344
	s_mov_b32 s4, s48
	v_lshl_or_b32 v0, s2, 10, v56
	v_lshl_add_u64 v[18:19], s[16:17], 0, v[0:1]
	s_movk_i32 s2, 0x2000
	v_add_co_u32_e32 v22, vcc, s2, v18
	s_movk_i32 s2, 0x4000
	s_nop 0
	v_addc_co_u32_e32 v23, vcc, 0, v19, vcc
	s_waitcnt lgkmcnt(0)
	s_barrier
	global_load_dwordx2 v[20:21], v0, s[16:17]
	global_load_dwordx2 v[24:25], v[22:23], off offset:-4096
	global_load_dwordx2 v[26:27], v[22:23], off
	v_add_co_u32_e32 v22, vcc, s2, v18
	s_movk_i32 s2, 0x6000
	s_nop 0
	v_addc_co_u32_e32 v23, vcc, 0, v19, vcc
	global_load_dwordx2 v[28:29], v[22:23], off offset:-4096
	global_load_dwordx2 v[30:31], v[22:23], off
	v_add_co_u32_e32 v22, vcc, s2, v18
	s_mov_b32 s2, 0x8000
	s_nop 0
	v_addc_co_u32_e32 v23, vcc, 0, v19, vcc
	global_load_dwordx2 v[32:33], v[22:23], off offset:-4096
	global_load_dwordx2 v[34:35], v[22:23], off
	v_add_co_u32_e32 v22, vcc, s2, v18
	s_mov_b32 s2, 0xa000
	s_nop 0
	v_addc_co_u32_e32 v23, vcc, 0, v19, vcc
	global_load_dwordx2 v[36:37], v[22:23], off offset:-4096
	global_load_dwordx2 v[38:39], v[22:23], off
	v_add_co_u32_e32 v22, vcc, s2, v18
	s_mov_b32 s2, 0xc000
	s_nop 0
	v_addc_co_u32_e32 v23, vcc, 0, v19, vcc
	global_load_dwordx2 v[40:41], v[22:23], off offset:-4096
	global_load_dwordx2 v[42:43], v[22:23], off
	v_add_co_u32_e32 v22, vcc, 0xb000, v18
	global_load_dwordx2 v[54:55], v0, s[0:1]
	s_nop 0
	v_addc_co_u32_e32 v23, vcc, 0, v19, vcc
	global_load_dwordx2 v[44:45], v[22:23], off
	v_add_co_u32_e32 v22, vcc, s2, v18
	v_mov_b32_e32 v56, 0
	s_nop 0
	v_addc_co_u32_e32 v23, vcc, 0, v19, vcc
	global_load_dwordx2 v[46:47], v[22:23], off
	v_add_co_u32_e32 v22, vcc, 0xd000, v18
	s_mov_b32 s2, 16
	s_nop 0
	v_addc_co_u32_e32 v23, vcc, 0, v19, vcc
	global_load_dwordx2 v[48:49], v[22:23], off
	v_add_co_u32_e32 v22, vcc, 0xe000, v18
	v_mov_b32_e32 v57, v56
	s_nop 0
	v_addc_co_u32_e32 v23, vcc, 0, v19, vcc
	global_load_dwordx2 v[50:51], v[22:23], off
	v_add_co_u32_e32 v22, vcc, 0xf000, v18
	s_nop 1
	v_addc_co_u32_e32 v23, vcc, 0, v19, vcc
	global_load_dwordx2 v[52:53], v[22:23], off
	v_lshl_add_u64 v[22:23], s[0:1], 0, v[0:1]
	v_mov_b32_e32 v0, v69
